# attention unit prologue: Q fragment loads issued right after the K/V DMA issue, before the bias-table section
# baseline (speedup 1.0000x reference)
; #define LAS __attribute__((address_space(3)))
; #define ISSUE_K(tile, slot) do { const int s_ = (tile) << 15; DMAB(kvo, s_, 0, (slot) * 16384 + kdma); DMAB(kvo, s_ + 8192, 0, (slot) * 16384 + 8192 + kdma); } while (0)
; #define ISSUE_V(tile, slot) do { const int s_ = (tile) << 15; DMAB(vvo, s_, 0, (slot) * 16384 + vdma); DMAB(vvo, s_ + 1024, 0, (slot) * 16384 + vdma + 1024); } while (0)
; __device__ __forceinline__ void attn_unit(LAS unsigned char* lds, bf16_t* Zg, const unsigned char* KVg, int S, int b, int h, int qb, const float* lq1, const float* lk1, const float* lq2, const float* lk2, const float* subln_g, const float* rel_bias, bool dostore = true) {
;     ...
;     const size_t rowbase = (size_t)b * S; const int q0 = qb * 128, qw0 = q0 + 32 * qsub;
;     LAS float* tab = (LAS float*)(lds + 131072);
;     LAS float* wsf = (LAS float*)(lds + 131072 + 2304) + wid * 32;
;     const int NT = S / 64; const size_t tstep = (size_t)64 * ZLD;
;     const unsigned char* kvb = KVg + ((size_t)((b * 8 + h) * NT) << 15);
;     const __amdgpu_buffer_rsrc_t kvr = __builtin_amdgcn_make_buffer_rsrc((void*)kvb, (short)0, NT << 15, 0x00020000);
;     const unsigned kvo = wid * 1024 + lane * 16;
;     const unsigned vvo = 16384 + (wid >> 1) * 4096 + (wid & 1) * 2048 + lane * 16;
;     const unsigned kdma = wid * 1024, vdma = 65536 + (wid >> 1) * 4096 + (wid & 1) * 2048;
;     ...
;     ISSUE_K(0, 0); ISSUE_V(0, 0); ISSUE_K(1, 1); ISSUE_K(2, 2); ISSUE_V(1, 1);
;     for (int ti = tid; ti < 513; ti += 512) { const int rel = ti - 256, n = rel < 0 ? -rel : rel;
;         int bk = n < 8 ? n : n < 12 ? 8 : n < 16 ? 9 : n < 23 ? 10 : n < 32 ? 11 : n < 46 ? 12 : n < 64 ? 13 : n < 91 ? 14 : 15; if (rel > 0) bk += 16;
;         tab[ti] = rel_bias[bk * 8 + h] * LOG2E; }
;     bf16x8 qr[4];
;     { const bf16_t* qp = Zg + (rowbase + qw0 + r32) * ZLD + COL_Q + mp * 512 + h * 64 + hi * 8;
; #pragma unroll
;       for (int d0 = 0; d0 < 4; ++d0) qr[d0] = *(const bf16x8*)(qp + d0 * 16); }
.LBB0_188:
	s_abs_i32 s5, s94
	s_mul_hi_u32 s6, s5, s34
	s_mul_i32 s7, s6, s66
	s_sub_i32 s5, s5, s7
	s_ashr_i32 s4, s94, 31
	s_add_i32 s7, s6, 1
	s_sub_i32 s8, s5, s66
	s_cmp_ge_u32 s5, s66
	s_cselect_b32 s6, s7, s6
	s_cselect_b32 s5, s8, s5
	s_add_i32 s7, s6, 1
	s_cmp_ge_u32 s5, s66
	s_cselect_b32 s5, s7, s6
	s_xor_b32 s5, s5, s4
	s_sub_i32 s28, s5, s4
	s_mov_b64 s[4:5], s[0:1]
	s_load_dwordx2 s[6:7], s[4:5], 0x98
	s_mov_b64 s[4:5], s[0:1]
	s_load_dwordx2 s[8:9], s[4:5], 0x98
	s_mov_b64 s[4:5], s[0:1]
	s_load_dwordx2 s[74:75], s[4:5], 0x20
	s_mov_b64 s[4:5], s[0:1]
	s_load_dwordx2 s[76:77], s[4:5], 0x28
	s_mov_b64 s[4:5], s[0:1]
	s_load_dwordx2 s[70:71], s[4:5], 0x30
	s_mov_b64 s[4:5], s[0:1]
	s_load_dwordx2 s[72:73], s[4:5], 0x38
	s_mov_b64 s[4:5], s[0:1]
	s_load_dwordx2 s[68:69], s[4:5], 0x40
	s_mov_b64 s[4:5], s[0:1]
	v_mov_b32_e32 v202, v204
	s_mul_i32 s12, s28, s67
	s_ashr_i32 s13, s12, 31
	v_readfirstlane_b32 s15, v202
	s_and_b32 s16, s28, 7
	s_ashr_i32 s29, s15, 6
	s_lshl_b64 s[12:13], s[12:13], 15
	s_waitcnt lgkmcnt(0)
	s_add_u32 s8, s8, s12
	s_addc_u32 s9, s9, s13
	s_add_u32 s20, s8, 0x29b00000
	v_and_b32_e32 v209, 63, v202
	s_addc_u32 s8, s9, 0
	s_lshl_b32 s9, s15, 5
	s_and_b32 s21, s8, 0xffff
	s_lshl_b32 s8, s29, 10
	v_lshlrev_b32_e32 v0, 4, v209
	s_and_b32 s9, s9, 0xfffff000
	s_lshl_b32 s10, s29, 11
	v_or_b32_e32 v224, s8, v0
	s_and_b32 s10, s10, 0x800
	s_add_i32 s42, s8, 0
	s_add_i32 s8, s9, 0
	s_or_b32 s12, s9, s10
	s_mov_b32 m0, s42
	s_add_i32 s50, s42, 0x2000
	s_add_i32 s25, s8, s10
	s_addk_i32 s12, 0x4000
	buffer_load_dwordx4 v224, s[20:23], 0 offen lds
	s_mov_b32 m0, s50
	s_add_i32 s57, s25, 0x10000
	v_or_b32_e32 v223, s12, v0
	buffer_load_dwordx4 v224, s[20:23], s87 offen lds
	s_mov_b32 m0, s57
	s_add_i32 s99, s25, 0x10400
	buffer_load_dwordx4 v223, s[20:23], 0 offen lds
	s_mov_b32 m0, s99
	s_movk_i32 s8, 0x400
	s_add_i32 s54, s42, 0x4000
	buffer_load_dwordx4 v223, s[20:23], s8 offen lds
	s_mov_b32 m0, s54
	s_mov_b32 s9, 0x8000
	s_add_i32 s55, s42, 0x6000
	buffer_load_dwordx4 v224, s[20:23], s9 offen lds
	s_mov_b32 m0, s55
	s_mov_b32 s8, 0xa000
	s_add_i32 s30, s42, 0x8000
	buffer_load_dwordx4 v224, s[20:23], s8 offen lds
	s_mov_b32 m0, s30
	s_mov_b32 s8, 0x10000
	s_add_i32 s10, s42, 0xa000
	buffer_load_dwordx4 v224, s[20:23], s8 offen lds
	s_mov_b32 m0, s10
	s_mov_b32 s8, 0x12000
	s_add_i32 s39, s25, 0x14000
	buffer_load_dwordx4 v224, s[20:23], s8 offen lds
	s_mov_b32 m0, s39
	s_add_i32 s25, s25, 0x14400
	buffer_load_dwordx4 v223, s[20:23], s9 offen lds
	s_mov_b32 m0, s25
	s_mov_b32 s8, 0x8400
	buffer_load_dwordx4 v223, s[20:23], s8 offen lds
	s_add_u32 s100, s6, 0x5a00000
	s_addc_u32 s101, s7, 0
	v_mov_b64_e32 v[36:37], s[100:101]
	s_mul_i32 s100, s28, s66
	s_sub_i32 s100, s94, s100
	s_lshl_b32 s100, s100, 7
	s_lshl_b32 s101, s29, 5
	s_and_b32 s101, s101, 0x60
	s_or_b32 s100, s100, s101
	s_ashr_i32 s101, s28, 3
	s_mul_i32 s101, s101, s11
	s_add_i32 s100, s100, s101
	v_and_b32_e32 v38, 31, v202
	v_add_u32_e32 v38, s100, v38
	s_ashr_i32 s100, s15, 8
	s_lshl_b32 s100, s100, 10
	s_lshl_b32 s101, s16, 7
	s_add_i32 s100, s100, s101
	v_mad_u64_u32 v[34:35], vcc, v38, s35, v[36:37]
	v_lshrrev_b32_e32 v38, 1, v202
	v_and_b32_e32 v38, 16, v38
	v_add_u32_e32 v38, s100, v38
	v_mov_b32_e32 v39, 0
	v_lshl_add_u64 v[34:35], v[34:35], 0, v[38:39]
	global_load_dwordx4 v[190:193], v[34:35], off
	global_load_dwordx4 v[186:189], v[34:35], off offset:32
	global_load_dwordx4 v[178:181], v[34:35], off offset:64
	global_load_dwordx4 v[182:185], v[34:35], off offset:96
	s_movk_i32 s8, 0x201
	v_cmp_gt_i32_e32 vcc, s8, v202
	s_and_saveexec_b64 s[8:9], vcc
	s_cbranch_execz .LBB0_206
	s_load_dwordx2 s[12:13], s[4:5], 0x88
	v_max_i32_e32 v0, 1, v202
	v_sub_u32_e32 v0, v0, v202
	v_add_u32_e32 v0, 0x1ff, v0
	s_movk_i32 s4, 0x1ff
	v_cmp_lt_u32_e32 vcc, s4, v0
	s_mov_b64 s[4:5], -1
	v_mov_b32_e32 v2, v202
	s_and_saveexec_b64 s[26:27], vcc
	s_cbranch_execz .LBB0_193
	v_lshrrev_b32_e32 v0, 9, v0
	v_add_u32_e32 v0, 1, v0
	v_and_b32_e32 v4, 0xfffffe, v0
	v_add_u32_e32 v203, 0x200, v202
	v_readlane_b32 s4, v246, 48
	s_mov_b32 s17, s16
	s_mov_b64 s[78:79], 0
	v_lshl_add_u32 v5, v202, 2, s4
	v_mov_b32_e32 v6, v4
	v_mov_b64_e32 v[2:3], v[202:203]

; #define LAS __attribute__((address_space(3)))
; #define NEAR_BIAS(C0, C1, k0v) do { if (!((((k0v) + 63 - qw0) <= -91) || (((k0v) - (qw0 + 31)) >= 91))) { const LAS float* tp_ = tab + ((k0v) + 4 * hi - (qw0 + r32) + 256);     \
;         _Pragma("unroll") for (int r = 0; r < 16; ++r) { C0[r] += tp_[(r & 3) + 8 * (r >> 2)]; C1[r] += tp_[(r & 3) + 8 * (r >> 2) + 32]; } } } while (0)
; #define SET_CINIT(k0v) do { const float ci_ = TILE_CB(k0v) - mhat; _Pragma("unroll") for (int r = 0; r < 16; ++r) cinit[r] = ci_; } while (0)
; __device__ __forceinline__ void attn_unit(LAS unsigned char* lds, bf16_t* Zg, const unsigned char* KVg, int S, int b, int h, int qb, const float* lq1, const float* lk1, const float* lq2, const float* lk2, const float* subln_g, const float* rel_bias, bool dostore = true) {
;     ...
;     bf16x8 qr[4];
;     { const bf16_t* qp = Zg + (rowbase + qw0 + r32) * ZLD + COL_Q + mp * 512 + h * 64 + hi * 8;
; #pragma unroll
;       for (int d0 = 0; d0 < 4; ++d0) qr[d0] = *(const bf16x8*)(qp + d0 * 16); }
;     asm volatile("s_waitcnt vmcnt(0)" ::: "memory");
;     __syncthreads();
;     const float c_neg = tab[0], c_pos = tab[512];
;     float mhat = 0.f, lsum = 0.f; f32x16 o[4]; o[0] = f32x16{}; o[1] = f32x16{}; o[2] = f32x16{}; o[3] = f32x16{};
;     const unsigned vlane = 65536 + (4 * hi + ((lane & 15) >> 2)) * 64 + ((lane >> 4) & 1) * 32 + (lane & 3) * 8;
;     unsigned kla[4];
; #pragma unroll
;     for (int d0 = 0; d0 < 4; ++d0) kla[d0] = mp * 8192 + r32 * 128 + (((2 * d0 + hi) ^ ((r32 >> 1) & 7)) << 4);
;     f32x16 cinit;
;     f32x16 pA0, pA1, pB0, pB1; u32x4 pw0, pw1, pw2, pw3;
;     ...
;     {
;         bf16x8 kf_[8]; const LAS unsigned char* kb_ = lds;
; #pragma unroll
;         for (int i_ = 0; i_ < 4; ++i_) { kf_[2 * i_] = *(const LAS bf16x8*)(kb_ + kla[i_]); kf_[2 * i_ + 1] = *(const LAS bf16x8*)(kb_ + kla[i_] + 4096); }
;         SET_CINIT(0);
; #pragma unroll
;         for (int i_ = 0; i_ < 8; ++i_) { if (i_ & 1) pA1 = __builtin_amdgcn_mfma_f32_32x32x16_bf16(kf_[i_], qr[i_ >> 1], (i_ < 2) ? cinit : pA1, 0, 0, 0);
;                                          else        pA0 = __builtin_amdgcn_mfma_f32_32x32x16_bf16(kf_[i_], qr[i_ >> 1], (i_ < 2) ? cinit : pA0, 0, 0, 0); }
;         NEAR_BIAS(pA0, pA1, 0);
.LBB0_206:
	s_or_b64 exec, exec, s[8:9]
	s_mul_i32 s4, s28, s66
	s_sub_i32 s4, s94, s4
	s_add_u32 s26, s6, 0x5a00000
	s_addc_u32 s27, s7, 0
	s_lshl_b32 s84, s29, 5
	s_ashr_i32 s82, s28, 3
	s_lshl_b32 s83, s4, 7
	s_and_b32 s85, s84, 0x60
	v_and_b32_e32 v210, 31, v202
	s_mul_hi_i32 s17, s82, s11
	s_mul_i32 s82, s82, s11
	s_or_b32 s78, s85, s83
	s_ashr_i32 s79, s78, 31
	v_or_b32_e32 v2, s82, v210
	v_mov_b32_e32 v3, s17
	v_lshl_add_u64 v[2:3], v[2:3], 0, s[78:79]
	v_mov_b64_e32 v[4:5], s[26:27]
	s_ashr_i32 s89, s15, 8
	v_mad_u64_u32 v[4:5], s[4:5], v2, s35, v[4:5]
	s_lshl_b32 s4, s89, 9
	v_mad_i32_i24 v5, v3, s35, v5
	s_ashr_i32 s5, s4, 31
	v_lshrrev_b32_e32 v38, 5, v209
	v_lshl_add_u64 v[2:3], s[4:5], 1, v[4:5]
	s_lshl_b32 s18, s16, 7
	v_lshl_add_u64 v[2:3], v[2:3], 0, s[18:19]
	v_lshlrev_b32_e32 v0, 4, v38
	v_lshl_add_u64 v[2:3], v[2:3], 0, v[0:1]
	v_lshrrev_b32_e32 v5, 1, v202
	v_lshlrev_b32_e32 v6, 7, v210
	v_bitop3_b32 v5, v38, v5, 7 bitop3:0x78
	v_lshl_or_b32 v39, s89, 13, v6
	v_readlane_b32 s4, v246, 48
	v_lshl_or_b32 v5, v5, 4, v39
	s_add_i32 s18, 0, 0x20000
	v_mov_b32_e32 v4, s4
	v_add_u32_e32 v216, 0, v5
	v_mov_b32_e32 v7, s18
	s_waitcnt vmcnt(0)
	s_waitcnt vmcnt(4) lgkmcnt(0)
	s_barrier
	ds_read_b32 v219, v4
	ds_read_b32 v218, v7
	ds_read_b128 v[34:37], v216
	s_cmpk_gt_i32 s78, 0x99
	s_cselect_b64 vcc, -1, 0
	s_cmpk_lt_i32 s78, 0xff87
	s_cselect_b64 s[4:5], -1, 0
	s_waitcnt lgkmcnt(2)
	v_cndmask_b32_e64 v2, 0, v219, s[4:5]
	s_waitcnt lgkmcnt(1)
	v_cndmask_b32_e32 v2, v2, v218, vcc
	v_mov_b32_e32 v3, v2
	v_mov_b32_e32 v4, v2
	v_mov_b32_e32 v5, v2
	v_mov_b32_e32 v6, v2
	v_mov_b32_e32 v7, v2
	v_mov_b32_e32 v8, v2
	v_mov_b32_e32 v9, v2
	v_mov_b32_e32 v10, v2
	v_mov_b32_e32 v11, v2
	v_mov_b32_e32 v12, v2
	v_mov_b32_e32 v13, v2
	v_mov_b32_e32 v14, v2
	v_mov_b32_e32 v15, v2
	v_mov_b32_e32 v16, v2
	v_mov_b32_e32 v17, v2
	v_bfe_u32 v40, v202, 1, 3
	v_bitop3_b32 v41, v38, v40, 2 bitop3:0x36
	v_lshl_or_b32 v41, v41, 4, v39
	v_add_u32_e32 v221, 0, v41
	v_bitop3_b32 v41, v38, v40, 4 bitop3:0x36
	v_lshl_or_b32 v41, v41, 4, v39
	v_add_u32_e32 v220, 0, v41
	v_bitop3_b32 v40, v38, v40, 6 bitop3:0x36
	v_lshl_or_b32 v39, v40, 4, v39
	v_add_u32_e32 v217, 0, v39
	s_add_i32 s4, s78, 0xffffff66
	v_lshlrev_b32_e32 v211, 2, v38
	s_cmp_gt_u32 s4, 0xfffffeec
	s_waitcnt vmcnt(3) lgkmcnt(0)
	v_mfma_f32_32x32x16_bf16 v[18:33], v[34:37], v[190:193], v[2:17]
	ds_read_b128 v[34:37], v216 offset:4096
	s_waitcnt lgkmcnt(0)
	v_mfma_f32_32x32x16_bf16 v[2:17], v[34:37], v[190:193], v[2:17]
	ds_read_b128 v[34:37], v221
	s_waitcnt vmcnt(2) lgkmcnt(0)
	v_mfma_f32_32x32x16_bf16 v[18:33], v[34:37], v[186:189], v[18:33]
	ds_read_b128 v[34:37], v221 offset:4096
	s_waitcnt lgkmcnt(0)
	v_mfma_f32_32x32x16_bf16 v[2:17], v[34:37], v[186:189], v[2:17]
	ds_read_b128 v[34:37], v220
	s_waitcnt vmcnt(1) lgkmcnt(0)
	v_mfma_f32_32x32x16_bf16 v[18:33], v[34:37], v[178:181], v[18:33]
	ds_read_b128 v[34:37], v220 offset:4096
	s_waitcnt lgkmcnt(0)
	v_mfma_f32_32x32x16_bf16 v[2:17], v[34:37], v[178:181], v[2:17]
	ds_read_b128 v[34:37], v217
	s_waitcnt vmcnt(0) lgkmcnt(0)
	v_mfma_f32_32x32x16_bf16 v[18:33], v[34:37], v[182:185], v[18:33]
	ds_read_b128 v[34:37], v217 offset:4096
	s_waitcnt lgkmcnt(0)
	v_mfma_f32_32x32x16_bf16 v[2:17], v[34:37], v[182:185], v[2:17]
	s_cbranch_scc0 .LBB0_208
	v_or_b32_e32 v34, s78, v210
	v_sub_u32_e32 v34, v211, v34
	v_lshl_add_u32 v62, v34, 2, s18
	v_add_u32_e32 v34, 0x400, v62
	v_add_u32_e32 v36, 0x480, v62
	ds_read2_b32 v[34:35], v34 offset1:1
	ds_read2_b32 v[36:37], v36 offset1:1
	v_add_u32_e32 v38, 0x408, v62
	v_add_u32_e32 v40, 0x488, v62
	v_add_u32_e32 v42, 0x420, v62
	v_add_u32_e32 v44, 0x4a0, v62
	v_add_u32_e32 v46, 0x428, v62
	v_add_u32_e32 v48, 0x4a8, v62
	v_add_u32_e32 v50, 0x440, v62
	v_add_u32_e32 v52, 0x4c0, v62
	v_add_u32_e32 v54, 0x448, v62
	v_add_u32_e32 v56, 0x4c8, v62
	v_add_u32_e32 v58, 0x460, v62
	v_add_u32_e32 v60, 0x4e0, v62
	v_add_u32_e32 v63, 0x468, v62
	v_add_u32_e32 v64, 0x4e8, v62
	ds_read2_b32 v[38:39], v38 offset1:1
	ds_read2_b32 v[40:41], v40 offset1:1
	ds_read2_b32 v[42:43], v42 offset1:1
	ds_read2_b32 v[44:45], v44 offset1:1
	ds_read2_b32 v[46:47], v46 offset1:1
	ds_read2_b32 v[48:49], v48 offset1:1
	ds_read2_b32 v[50:51], v50 offset1:1
	ds_read2_b32 v[52:53], v52 offset1:1
	ds_read2_b32 v[54:55], v54 offset1:1
	ds_read2_b32 v[56:57], v56 offset1:1
	ds_read2_b32 v[58:59], v58 offset1:1
	ds_read2_b32 v[60:61], v60 offset1:1
	ds_read2_b32 v[62:63], v63 offset1:1
	s_waitcnt lgkmcnt(14)
	v_pk_add_f32 v[18:19], v[18:19], v[34:35]
	ds_read2_b32 v[34:35], v64 offset1:1
	s_waitcnt lgkmcnt(3)
	v_pk_add_f32 v[30:31], v[30:31], v[58:59]
	v_pk_add_f32 v[28:29], v[28:29], v[54:55]
	s_waitcnt lgkmcnt(1)
	v_pk_add_f32 v[32:33], v[32:33], v[62:63]
	v_pk_add_f32 v[26:27], v[26:27], v[50:51]
	v_pk_add_f32 v[24:25], v[24:25], v[46:47]
	v_pk_add_f32 v[22:23], v[22:23], v[42:43]
	v_pk_add_f32 v[20:21], v[20:21], v[38:39]
	s_waitcnt lgkmcnt(0)
	v_pk_add_f32 v[16:17], v[16:17], v[34:35]
	v_pk_add_f32 v[14:15], v[14:15], v[60:61]
	v_pk_add_f32 v[12:13], v[12:13], v[56:57]
	v_pk_add_f32 v[10:11], v[10:11], v[52:53]
	v_pk_add_f32 v[8:9], v[8:9], v[48:49]
	v_pk_add_f32 v[6:7], v[6:7], v[44:45]
	v_pk_add_f32 v[4:5], v[4:5], v[40:41]
	v_pk_add_f32 v[2:3], v[2:3], v[36:37]

; __global__ void __launch_bounds__(NTHREADS, 2) fwd_megakernel(Params P, int ph_lo, int ph_hi, int use_sync) {
	.amdhsa_kernel _Z14fwd_megakernel6Paramsiii
		.amdhsa_group_segment_fixed_size 0
		.amdhsa_private_segment_fixed_size 0
		.amdhsa_kernarg_size 432
		.amdhsa_user_sgpr_count 2
		.amdhsa_user_sgpr_dispatch_ptr 0
		.amdhsa_user_sgpr_queue_ptr 0
		.amdhsa_user_sgpr_kernarg_segment_ptr 1
		.amdhsa_user_sgpr_dispatch_id 0
		.amdhsa_user_sgpr_kernarg_preload_length 0
		.amdhsa_user_sgpr_kernarg_preload_offset 0
		.amdhsa_user_sgpr_private_segment_size 0
		.amdhsa_uses_dynamic_stack 0
		.amdhsa_enable_private_segment 0
		.amdhsa_system_sgpr_workgroup_id_x 1
		.amdhsa_system_sgpr_workgroup_id_y 0
		.amdhsa_system_sgpr_workgroup_id_z 0
		.amdhsa_system_sgpr_workgroup_info 0
		.amdhsa_system_vgpr_workitem_id 2
		.amdhsa_next_free_vgpr 248
		.amdhsa_next_free_sgpr 102
		.amdhsa_accum_offset 248
		.amdhsa_reserve_vcc 1
		.amdhsa_float_round_mode_32 0
		.amdhsa_float_round_mode_16_64 0
		.amdhsa_float_denorm_mode_32 3
		.amdhsa_float_denorm_mode_16_64 3
		.amdhsa_dx10_clamp 1
		.amdhsa_ieee_mode 1
		.amdhsa_fp16_overflow 0
		.amdhsa_tg_split 0
		.amdhsa_exception_fp_ieee_invalid_op 0
		.amdhsa_exception_fp_denorm_src 0
		.amdhsa_exception_fp_ieee_div_zero 0
		.amdhsa_exception_fp_ieee_overflow 0
		.amdhsa_exception_fp_ieee_underflow 0
		.amdhsa_exception_fp_ieee_inexact 0
		.amdhsa_exception_int_div_zero 0
	.end_amdhsa_kernel

; __global__ void __launch_bounds__(NTHREADS, 2) fwd_megakernel(Params P, int ph_lo, int ph_hi, int use_sync) {
amdhsa.kernels:
  - .agpr_count:     0
    .args:
      - .offset:         0
        .size:           160
        .value_kind:     by_value
      - .offset:         160
        .size:           4
        .value_kind:     by_value
      - .offset:         164
        .size:           4
        .value_kind:     by_value
      - .offset:         168
        .size:           4
        .value_kind:     by_value
      - .offset:         176
        .size:           4
        .value_kind:     hidden_block_count_x
      - .offset:         180
        .size:           4
        .value_kind:     hidden_block_count_y
      - .offset:         184
        .size:           4
        .value_kind:     hidden_block_count_z
      - .offset:         188
        .size:           2
        .value_kind:     hidden_group_size_x
      - .offset:         190
        .size:           2
        .value_kind:     hidden_group_size_y
      - .offset:         192
        .size:           2
        .value_kind:     hidden_group_size_z
      - .offset:         194
        .size:           2
        .value_kind:     hidden_remainder_x
      - .offset:         196
        .size:           2
        .value_kind:     hidden_remainder_y
      - .offset:         198
        .size:           2
        .value_kind:     hidden_remainder_z
      - .offset:         216
        .size:           8
        .value_kind:     hidden_global_offset_x
      - .offset:         224
        .size:           8
        .value_kind:     hidden_global_offset_y
      - .offset:         232
        .size:           8
        .value_kind:     hidden_global_offset_z
      - .offset:         240
        .size:           2
        .value_kind:     hidden_grid_dims
      - .offset:         264
        .size:           8
        .value_kind:     hidden_multigrid_sync_arg
      - .offset:         296
        .size:           4
        .value_kind:     hidden_dynamic_lds_size
    .group_segment_fixed_size: 0
    .kernarg_segment_align: 8
    .kernarg_segment_size: 432
    .language:       OpenCL C
    .language_version:
      - 2
      - 0
    .max_flat_workgroup_size: 512
    .name:           _Z14fwd_megakernel6Paramsiii
    .private_segment_fixed_size: 0
    .sgpr_count:     108
    .sgpr_spill_count: 108
    .symbol:         _Z14fwd_megakernel6Paramsiii.kd
    .uniform_work_group_size: 1
    .uses_dynamic_stack: false
    .vgpr_count:     248
    .vgpr_spill_count: 0
    .wavefront_size: 64
